# attention loop: counted lgkmcnt(4) waits per K/V fragment group instead of lgkmcnt(0) right after issuing the next group's ds_reads (LDS latency no longer exposed 7x per tile)
# baseline (speedup 1.0000x reference)
; #define LAS __attribute__((address_space(3)))
; #define AT_LDK(buf, grp) do { _Pragma("unroll") for (int q_ = 0; q_ < 2; ++q_) { kf[buf][2 * q_] = *(const LAS bf16x8*)(ka + ((grp) * 2 + q_) * 32); kf[buf][2 * q_ + 1] = *(const LAS bf16x8*)(ka + 32 * AT_KROW + ((grp) * 2 + q_) * 32); } } while (0)
; #define AT_LDV(buf, hs) do { const LAS unsigned char* vp_ = va + ((((hs) >> 1) >> 1) * 32 + 16 * (((hs) >> 1) & 1)) * AT_VROW + ((hs) & 1) * 128; _Pragma("unroll") for (int d_ = 0; d_ < 2; ++d_) { vf[buf][2 * d_] = vtr(vp_ + d_ * 64); vf[buf][2 * d_ + 1] = vtr(vp_ + 8 * AT_VROW + d_ * 64); } } while (0)
; __device__ __forceinline__ void attn_phase(LAS unsigned char* lds, const bf16* Q, const bf16* KV, const bf16* KPE, const float* rope, bf16* mix, int bid, int G, int tid) {
;     ...
;             if (key0 <= qlo + 31) {
;                 f32x16 S0, S1;
; #pragma unroll
;                 for (int e = 0; e < 16; ++e) { S0[e] = 0.f; S1[e] = 0.f; }
;                 const LAS unsigned char* ka = kb_ + l32 * AT_KROW + hh * 16;
;                 bf16x8 kf[2][4];
;     ...
;                 AT_LDK(0, 0); __builtin_amdgcn_sched_barrier(0);
; #pragma unroll
;                 for (int grp = 0; grp < 6; ++grp) {
;                     if (grp < 5) { AT_LDK((grp + 1) & 1, grp + 1); }
;                     __builtin_amdgcn_sched_barrier(0);
;                     __builtin_amdgcn_s_setprio(1);
; #pragma unroll
;                     for (int q_ = 0; q_ < 2; ++q_) {
;                         S0 = __builtin_amdgcn_mfma_f32_32x32x16_bf16(kf[grp & 1][2 * q_], qf[grp * 2 + q_], S0, 0, 0, 0);
;                         S1 = __builtin_amdgcn_mfma_f32_32x32x16_bf16(kf[grp & 1][2 * q_ + 1], qf[grp * 2 + q_], S1, 0, 0, 0); }
;                     __builtin_amdgcn_s_setprio(0);
;                     __builtin_amdgcn_sched_barrier(0); }
;     ...
;                 const LAS unsigned char* va = vb_ + (4 * hh + ((lane & 15) >> 2)) * AT_VROW + (16 * ((lane >> 4) & 1) + 4 * (lane & 3)) * 2;
;                 s16x4 vf[2][4];
;     ...
;                 AT_LDV(0, 0); __builtin_amdgcn_sched_barrier(0);
.LBB0_253:
	s_sub_i32 s5, s0, 63
	s_cmp_gt_i32 s5, s11
	s_cbranch_scc1 .LBB0_259
	s_bitcmp1_b32 s4, 0
	s_cselect_b32 s4, 0xb400, 0
	s_add_i32 s4, s4, 0
	v_add3_u32 v236, s4, v203, v96
	ds_read_b128 v[64:67], v236
	ds_read_b128 v[166:169], v236 offset:32
	ds_read_b128 v[68:71], v236 offset:12800
	ds_read_b128 v[170:173], v236 offset:12832
	ds_read_b128 v[208:211], v236 offset:64
	ds_read_b128 v[212:215], v236 offset:96
	ds_read_b128 v[228:231], v236 offset:12864
	ds_read_b128 v[232:235], v236 offset:12896
	s_setprio 1
	s_waitcnt lgkmcnt(4)
	v_mfma_f32_32x32x16_bf16 v[80:95], v[64:67], v[98:101], 0
	v_mfma_f32_32x32x16_bf16 v[64:79], v[68:71], v[98:101], 0
	v_mfma_f32_32x32x16_bf16 v[80:95], v[166:169], v[102:105], v[80:95]
	v_mfma_f32_32x32x16_bf16 v[64:79], v[170:173], v[102:105], v[64:79]
	s_setprio 0
	ds_read_b128 v[166:169], v236 offset:128
	ds_read_b128 v[170:173], v236 offset:160
	ds_read_b128 v[242:245], v236 offset:12928
	ds_read_b128 v[246:249], v236 offset:12960
	s_setprio 1
	s_waitcnt lgkmcnt(4)
	v_mfma_f32_32x32x16_bf16 v[80:95], v[208:211], v[106:109], v[80:95]
	v_mfma_f32_32x32x16_bf16 v[64:79], v[228:231], v[106:109], v[64:79]
	v_mfma_f32_32x32x16_bf16 v[80:95], v[212:215], v[110:113], v[80:95]
	v_mfma_f32_32x32x16_bf16 v[64:79], v[232:235], v[110:113], v[64:79]
	s_setprio 0
	ds_read_b128 v[208:211], v236 offset:192
	ds_read_b128 v[212:215], v236 offset:224
	ds_read_b128 v[228:231], v236 offset:12992
	ds_read_b128 v[232:235], v236 offset:13024
	s_setprio 1
	s_waitcnt lgkmcnt(4)
	v_mfma_f32_32x32x16_bf16 v[80:95], v[166:169], v[114:117], v[80:95]
	v_mfma_f32_32x32x16_bf16 v[64:79], v[242:245], v[114:117], v[64:79]
	v_mfma_f32_32x32x16_bf16 v[80:95], v[170:173], v[118:121], v[80:95]
	v_mfma_f32_32x32x16_bf16 v[64:79], v[246:249], v[118:121], v[64:79]
	s_setprio 0
	ds_read_b128 v[166:169], v236 offset:256
	ds_read_b128 v[170:173], v236 offset:288
	ds_read_b128 v[242:245], v236 offset:13056
	ds_read_b128 v[246:249], v236 offset:13088
	s_setprio 1
	s_waitcnt lgkmcnt(4)
	v_mfma_f32_32x32x16_bf16 v[80:95], v[208:211], v[122:125], v[80:95]
	v_mfma_f32_32x32x16_bf16 v[64:79], v[228:231], v[122:125], v[64:79]
	v_mfma_f32_32x32x16_bf16 v[80:95], v[212:215], v[126:129], v[80:95]
	v_mfma_f32_32x32x16_bf16 v[64:79], v[232:235], v[126:129], v[64:79]
	s_setprio 0
	ds_read_b128 v[208:211], v236 offset:320
	ds_read_b128 v[212:215], v236 offset:352
	ds_read_b128 v[228:231], v236 offset:13120
	ds_read_b128 v[232:235], v236 offset:13152
	s_setprio 1
	s_waitcnt lgkmcnt(4)
	v_mfma_f32_32x32x16_bf16 v[80:95], v[166:169], v[130:133], v[80:95]
	v_mfma_f32_32x32x16_bf16 v[64:79], v[242:245], v[130:133], v[64:79]
	v_mfma_f32_32x32x16_bf16 v[80:95], v[170:173], v[158:161], v[80:95]
	v_mfma_f32_32x32x16_bf16 v[64:79], v[246:249], v[158:161], v[64:79]
	s_setprio 0
	s_setprio 1
	s_setprio 0
	s_waitcnt lgkmcnt(0)
	v_mfma_f32_32x32x16_bf16 v[80:95], v[208:211], v[134:137], v[80:95]
	v_add_u32_e32 v166, s4, v204
	v_add_u32_e32 v208, v166, v205
	ds_read_b64_tr_b16 v[170:171], v208 offset:25600
	ds_read_b64_tr_b16 v[172:173], v208 offset:28160
	ds_read_b64_tr_b16 v[168:169], v208 offset:28224
	ds_read_b64_tr_b16 v[166:167], v208 offset:25664
	v_mfma_f32_32x32x16_bf16 v[64:79], v[228:231], v[134:137], v[64:79]
	v_mfma_f32_32x32x16_bf16 v[80:95], v[212:215], v[162:165], v[80:95]
	v_mfma_f32_32x32x16_bf16 v[64:79], v[232:235], v[162:165], v[64:79]
	s_cmp_le_i32 s0, s8
	s_cbranch_scc1 .LBB0_256
; __device__ __forceinline__ void attn_phase(LAS unsigned char* lds, const bf16* Q, const bf16* KV, const bf16* KPE, const float* rope, bf16* mix, int bid, int G, int tid) {
;     ...
;                 if (key0 + 63 > qlo) { const int qq = qlo + l32;
; #pragma unroll
;                     for (int e = 0; e < 16; ++e) { const int key = key0 + 8 * (e >> 2) + 4 * hh + (e & 3);
;                         if (key > qq) S0[e] = -1e30f; if (key + 32 > qq) S1[e] = -1e30f; } }
	v_add_u32_e32 v209, s0, v189
	v_subrev_u32_e32 v211, 31, v209
	v_subrev_u32_e32 v210, 63, v209
	v_cmp_le_i32_e32 vcc, v211, v206
	s_nop 5
	v_cndmask_b32_e32 v64, v224, v64, vcc
	v_cmp_lt_i32_e32 vcc, v210, v206
	s_nop 1
	v_cndmask_b32_e32 v81, v224, v81, vcc
	v_cmp_le_i32_e32 vcc, v210, v206
	v_subrev_u32_e32 v210, 30, v209
	s_nop 0
	v_cndmask_b32_e32 v80, v224, v80, vcc
	v_cmp_le_i32_e32 vcc, v210, v206
	v_subrev_u32_e32 v210, 61, v209
	s_nop 0
	v_cndmask_b32_e32 v65, v224, v65, vcc
	v_cmp_le_i32_e32 vcc, v210, v206
	v_subrev_u32_e32 v210, 29, v209
	s_nop 0
	v_cndmask_b32_e32 v82, v224, v82, vcc
	v_cmp_le_i32_e32 vcc, v210, v206
	v_subrev_u32_e32 v210, 60, v209
	s_nop 0
	v_cndmask_b32_e32 v66, v224, v66, vcc
	v_cmp_le_i32_e32 vcc, v210, v206
	v_subrev_u32_e32 v210, 28, v209
	s_nop 0
	v_cndmask_b32_e32 v83, v224, v83, vcc
	v_cmp_le_i32_e32 vcc, v210, v206
	v_subrev_u32_e32 v210, 55, v209
	s_nop 0
	v_cndmask_b32_e32 v67, v224, v67, vcc
	v_cmp_le_i32_e32 vcc, v210, v206
	v_subrev_u32_e32 v210, 23, v209
	s_nop 0
	v_cndmask_b32_e32 v84, v224, v84, vcc
	v_cmp_le_i32_e32 vcc, v210, v206
	v_subrev_u32_e32 v210, 54, v209
	s_nop 0
	v_cndmask_b32_e32 v68, v224, v68, vcc
	v_cmp_le_i32_e32 vcc, v210, v206
	v_subrev_u32_e32 v210, 22, v209
	s_nop 0
	v_cndmask_b32_e32 v85, v224, v85, vcc
	v_cmp_le_i32_e32 vcc, v210, v206
	v_subrev_u32_e32 v210, 53, v209
	s_nop 0
	v_cndmask_b32_e32 v69, v224, v69, vcc
	v_cmp_le_i32_e32 vcc, v210, v206
	v_subrev_u32_e32 v210, 21, v209
	s_nop 0
	v_cndmask_b32_e32 v86, v224, v86, vcc
	v_cmp_le_i32_e32 vcc, v210, v206
	v_subrev_u32_e32 v210, 52, v209
	s_nop 0
	v_cndmask_b32_e32 v70, v224, v70, vcc
	v_cmp_le_i32_e32 vcc, v210, v206
	v_subrev_u32_e32 v210, 20, v209
	s_nop 0
	v_cndmask_b32_e32 v87, v224, v87, vcc
	v_cmp_le_i32_e32 vcc, v210, v206
	v_subrev_u32_e32 v210, 47, v209
	s_nop 0
	v_cndmask_b32_e32 v71, v224, v71, vcc
	v_cmp_le_i32_e32 vcc, v210, v206
	v_add_u32_e32 v210, -15, v209
	s_nop 0
	v_cndmask_b32_e32 v88, v224, v88, vcc
	v_cmp_le_i32_e32 vcc, v210, v206
	v_subrev_u32_e32 v210, 46, v209
	s_nop 0
	v_cndmask_b32_e32 v72, v224, v72, vcc
	v_cmp_le_i32_e32 vcc, v210, v206
	v_add_u32_e32 v210, -14, v209
	s_nop 0
	v_cndmask_b32_e32 v89, v224, v89, vcc
	v_cmp_le_i32_e32 vcc, v210, v206
	v_subrev_u32_e32 v210, 45, v209
	s_nop 0
	v_cndmask_b32_e32 v73, v224, v73, vcc
	v_cmp_le_i32_e32 vcc, v210, v206
	v_add_u32_e32 v210, -13, v209
	s_nop 0
	v_cndmask_b32_e32 v90, v224, v90, vcc
	v_cmp_le_i32_e32 vcc, v210, v206
	v_subrev_u32_e32 v210, 44, v209
	s_nop 0
	v_cndmask_b32_e32 v74, v224, v74, vcc
	v_cmp_le_i32_e32 vcc, v210, v206
	v_add_u32_e32 v210, -12, v209
	s_nop 0
	v_cndmask_b32_e32 v91, v224, v91, vcc
	v_cmp_le_i32_e32 vcc, v210, v206
	v_subrev_u32_e32 v210, 39, v209
	s_nop 0
	v_cndmask_b32_e32 v75, v224, v75, vcc
	v_cmp_le_i32_e32 vcc, v210, v206
	v_add_u32_e32 v210, -7, v209
	s_nop 0
	v_cndmask_b32_e32 v92, v224, v92, vcc
	v_cmp_le_i32_e32 vcc, v210, v206
	v_subrev_u32_e32 v210, 38, v209
	s_nop 0
	v_cndmask_b32_e32 v76, v224, v76, vcc
	v_cmp_le_i32_e32 vcc, v210, v206
	v_add_u32_e32 v210, -6, v209
	s_nop 0
	v_cndmask_b32_e32 v93, v224, v93, vcc
	v_cmp_le_i32_e32 vcc, v210, v206
	v_subrev_u32_e32 v210, 37, v209
	s_nop 0
	v_cndmask_b32_e32 v77, v224, v77, vcc
	v_cmp_le_i32_e32 vcc, v210, v206
	v_add_u32_e32 v210, -5, v209
	s_nop 0
	v_cndmask_b32_e32 v94, v224, v94, vcc
	v_cmp_le_i32_e32 vcc, v210, v206
	v_subrev_u32_e32 v210, 36, v209
	v_add_u32_e32 v209, -4, v209
	v_cndmask_b32_e32 v78, v224, v78, vcc
	v_cmp_le_i32_e32 vcc, v210, v206
	s_nop 1
	v_cndmask_b32_e32 v95, v224, v95, vcc
	v_cmp_le_i32_e32 vcc, v209, v206
	s_nop 1
	v_cndmask_b32_e32 v79, v224, v79, vcc

; __device__ __forceinline__ u32x4 pack8(const float (&f)[8]) { u32x4 w; w.x = pk_bf16(f[0], f[1]); w.y = pk_bf16(f[2], f[3]); w.z = pk_bf16(f[4], f[5]); w.w = pk_bf16(f[6], f[7]); return w; }
; #define AT_LDV(buf, hs) do { const LAS unsigned char* vp_ = va + ((((hs) >> 1) >> 1) * 32 + 16 * (((hs) >> 1) & 1)) * AT_VROW + ((hs) & 1) * 128; _Pragma("unroll") for (int d_ = 0; d_ < 2; ++d_) { vf[buf][2 * d_] = vtr(vp_ + d_ * 64); vf[buf][2 * d_ + 1] = vtr(vp_ + 8 * AT_VROW + d_ * 64); } } while (0)
; __device__ __forceinline__ void attn_phase(LAS unsigned char* lds, const bf16* Q, const bf16* KV, const bf16* KPE, const float* rope, bf16* mix, int bid, int G, int tid) {
;     ...
;                 const float alpha = __builtin_amdgcn_exp2f(mrun - mnew); mrun = mnew;
;                 float rs = 0.f;
; #pragma unroll
;                 for (int e = 0; e < 16; ++e) { S0[e] = __builtin_amdgcn_exp2f(S0[e] - mnew); S1[e] = __builtin_amdgcn_exp2f(S1[e] - mnew); rs += S0[e] + S1[e]; }
;                 lrun = lrun * alpha + rs;
;                 if (__builtin_amdgcn_ballot_w64(alpha != 1.0f) != 0ull) {
; #pragma unroll
;                     for (int i = 0; i < 4; ++i)
; #pragma unroll
;                         for (int e = 0; e < 16; ++e) O[i][e] *= alpha; }
; #pragma unroll
;                 for (int hs = 0; hs < 8; ++hs) { const int st = hs >> 1;
;                     if (hs < 7) { AT_LDV((hs + 1) & 1, hs + 1); }
;                     __builtin_amdgcn_sched_barrier(0);
;                     float pf[8];
; #pragma unroll
;                     for (int e = 0; e < 8; ++e) pf[e] = (st >> 1) ? S1[8 * (st & 1) + e] : S0[8 * (st & 1) + e];
;                     const bf16x8 pb = __builtin_bit_cast(bf16x8, pack8(pf));
; #pragma unroll
;                     for (int d_ = 0; d_ < 2; ++d_) { const int dvt = (hs & 1) * 2 + d_; const s16x4 lo = vf[hs & 1][2 * d_], hi = vf[hs & 1][2 * d_ + 1];
;                         const bf16x8 A = (bf16x8){lo[0], lo[1], lo[2], lo[3], hi[0], hi[1], hi[2], hi[3]};
;                         __builtin_amdgcn_s_setprio(1); O[dvt] = __builtin_amdgcn_mfma_f32_32x32x16_bf16(A, pb, O[dvt], 0, 0, 0); __builtin_amdgcn_s_setprio(0); }
;                     __builtin_amdgcn_sched_barrier(0); }
.LBB0_258:
	v_sub_f32_e32 v80, v80, v209
	v_sub_f32_e32 v64, v64, v209
	v_exp_f32_e32 v80, v80
	v_exp_f32_e32 v210, v64
	v_sub_f32_e32 v81, v81, v209
	v_sub_f32_e32 v65, v65, v209
	v_exp_f32_e32 v81, v81
	v_exp_f32_e32 v211, v65
	v_add_f32_e32 v64, v80, v210
	v_add_f32_e32 v64, 0, v64
	v_add_f32_e32 v65, v81, v211
	v_add_f32_e32 v64, v65, v64
	v_sub_f32_e32 v65, v82, v209
	v_exp_f32_e32 v82, v65
	v_sub_f32_e32 v65, v66, v209
	v_exp_f32_e32 v212, v65
	s_nop 0
	v_add_f32_e32 v65, v82, v212
	v_add_f32_e32 v64, v65, v64
	v_sub_f32_e32 v65, v83, v209
	v_exp_f32_e32 v83, v65
	v_sub_f32_e32 v65, v67, v209
	v_exp_f32_e32 v213, v65
	s_nop 0
	v_add_f32_e32 v65, v83, v213
	v_add_f32_e32 v64, v65, v64
	v_sub_f32_e32 v65, v84, v209
	v_exp_f32_e32 v84, v65
	v_sub_f32_e32 v65, v68, v209
	v_exp_f32_e32 v214, v65
	s_nop 0
	v_add_f32_e32 v65, v84, v214
	v_add_f32_e32 v64, v65, v64
	v_sub_f32_e32 v65, v85, v209
	v_exp_f32_e32 v85, v65
	v_sub_f32_e32 v65, v69, v209
	v_exp_f32_e32 v215, v65
	s_nop 0
	v_add_f32_e32 v65, v85, v215
	v_add_f32_e32 v64, v65, v64
	v_sub_f32_e32 v65, v86, v209
	v_exp_f32_e32 v86, v65
	v_sub_f32_e32 v65, v70, v209
	v_exp_f32_e32 v228, v65
	s_nop 0
	v_add_f32_e32 v65, v86, v228
	v_add_f32_e32 v64, v65, v64
	v_sub_f32_e32 v65, v87, v209
	v_exp_f32_e32 v87, v65
	v_sub_f32_e32 v65, v71, v209
	v_exp_f32_e32 v229, v65
	s_nop 0
	v_add_f32_e32 v65, v87, v229
	v_add_f32_e32 v64, v65, v64
	v_sub_f32_e32 v65, v88, v209
	v_exp_f32_e32 v88, v65
	v_sub_f32_e32 v65, v72, v209
	v_exp_f32_e32 v230, v65
	s_nop 0
	v_add_f32_e32 v65, v88, v230
	v_add_f32_e32 v64, v65, v64
	v_sub_f32_e32 v65, v89, v209
	v_exp_f32_e32 v89, v65
	v_sub_f32_e32 v65, v73, v209
	v_exp_f32_e32 v231, v65
	s_nop 0
	v_add_f32_e32 v65, v89, v231
	v_add_f32_e32 v64, v65, v64
	v_sub_f32_e32 v65, v90, v209
	v_exp_f32_e32 v90, v65
	v_sub_f32_e32 v65, v74, v209
	v_exp_f32_e32 v232, v65
	s_nop 0
	v_add_f32_e32 v65, v90, v232
	v_add_f32_e32 v64, v65, v64
	v_sub_f32_e32 v65, v91, v209
	v_exp_f32_e32 v91, v65
	v_sub_f32_e32 v65, v75, v209
	v_exp_f32_e32 v233, v65
	s_nop 0
	v_add_f32_e32 v65, v91, v233
	v_add_f32_e32 v64, v65, v64
	v_sub_f32_e32 v65, v92, v209
	v_exp_f32_e32 v92, v65
	v_sub_f32_e32 v65, v76, v209
	v_exp_f32_e32 v234, v65
	s_nop 0
	v_add_f32_e32 v65, v92, v234
	v_add_f32_e32 v64, v65, v64
	v_sub_f32_e32 v65, v93, v209
	v_exp_f32_e32 v93, v65
	v_sub_f32_e32 v65, v77, v209
	v_exp_f32_e32 v235, v65
	s_nop 0
	v_add_f32_e32 v65, v93, v235
	v_add_f32_e32 v64, v65, v64
	v_sub_f32_e32 v65, v94, v209
	v_exp_f32_e32 v94, v65
	v_sub_f32_e32 v65, v78, v209
	v_exp_f32_e32 v236, v65
	s_nop 0
	v_add_f32_e32 v65, v94, v236
	v_add_f32_e32 v64, v65, v64
	v_sub_f32_e32 v65, v95, v209
	v_exp_f32_e32 v95, v65
	v_sub_f32_e32 v65, v79, v209
	v_exp_f32_e32 v237, v65
	s_nop 0
	v_add_f32_e32 v65, v95, v237
	v_add_f32_e32 v242, v65, v64
	ds_read_b64_tr_b16 v[64:65], v208 offset:25728
	ds_read_b64_tr_b16 v[66:67], v208 offset:28288
	ds_read_b64_tr_b16 v[68:69], v208 offset:25792
	ds_read_b64_tr_b16 v[70:71], v208 offset:28352
	v_fmac_f32_e32 v242, v207, v184
	v_cvt_pk_bf16_f32 v72, v80, v81
	v_cvt_pk_bf16_f32 v73, v82, v83
	v_cvt_pk_bf16_f32 v74, v84, v85
	v_cvt_pk_bf16_f32 v75, v86, v87
	s_setprio 1
	s_nop 0
	v_mfma_f32_32x32x16_bf16 v[48:63], v[170:173], v[72:75], v[48:63]
	s_setprio 0
	s_setprio 1
	v_mfma_f32_32x32x16_bf16 v[32:47], v[166:169], v[72:75], v[32:47]
	s_setprio 0
	ds_read_b64_tr_b16 v[76:77], v208 offset:30720
	ds_read_b64_tr_b16 v[78:79], v208 offset:33280
	ds_read_b64_tr_b16 v[80:81], v208 offset:30784
	ds_read_b64_tr_b16 v[82:83], v208 offset:33344
	s_setprio 1
	s_waitcnt lgkmcnt(4)
	v_mfma_f32_32x32x16_bf16 v[16:31], v[64:67], v[72:75], v[16:31]
	s_setprio 0
	s_setprio 1
	v_mfma_f32_32x32x16_bf16 v[0:15], v[68:71], v[72:75], v[0:15]
	s_setprio 0
	ds_read_b64_tr_b16 v[64:65], v208 offset:30848
	ds_read_b64_tr_b16 v[66:67], v208 offset:33408
	ds_read_b64_tr_b16 v[68:69], v208 offset:30912
	ds_read_b64_tr_b16 v[70:71], v208 offset:33472
	v_cvt_pk_bf16_f32 v72, v88, v89
	v_cvt_pk_bf16_f32 v73, v90, v91
	v_cvt_pk_bf16_f32 v74, v92, v93
	v_cvt_pk_bf16_f32 v75, v94, v95
	s_setprio 1
	s_nop 0
	s_waitcnt lgkmcnt(4)
	v_mfma_f32_32x32x16_bf16 v[48:63], v[76:79], v[72:75], v[48:63]
	s_setprio 0
	s_setprio 1
	v_mfma_f32_32x32x16_bf16 v[32:47], v[80:83], v[72:75], v[32:47]
	s_setprio 0
	ds_read_b64_tr_b16 v[76:77], v208 offset:35840
	ds_read_b64_tr_b16 v[78:79], v208 offset:38400
	ds_read_b64_tr_b16 v[82:83], v208 offset:38464
	ds_read_b64_tr_b16 v[80:81], v208 offset:35904
	s_setprio 1
	s_waitcnt lgkmcnt(4)
	v_mfma_f32_32x32x16_bf16 v[16:31], v[64:67], v[72:75], v[16:31]
	s_setprio 0
	s_setprio 1
	v_mfma_f32_32x32x16_bf16 v[0:15], v[68:71], v[72:75], v[0:15]
	s_setprio 0
	ds_read_b64_tr_b16 v[64:65], v208 offset:35968
	ds_read_b64_tr_b16 v[66:67], v208 offset:38528
	ds_read_b64_tr_b16 v[70:71], v208 offset:38592
	ds_read_b64_tr_b16 v[68:69], v208 offset:36032
	v_cvt_pk_bf16_f32 v72, v210, v211
	v_cvt_pk_bf16_f32 v73, v212, v213
	v_cvt_pk_bf16_f32 v74, v214, v215
	v_cvt_pk_bf16_f32 v75, v228, v229
	s_setprio 1
	s_nop 0
	s_waitcnt lgkmcnt(4)
	v_mfma_f32_32x32x16_bf16 v[48:63], v[76:79], v[72:75], v[48:63]
	s_setprio 0
	s_setprio 1
	v_mfma_f32_32x32x16_bf16 v[32:47], v[80:83], v[72:75], v[32:47]
	s_setprio 0
	ds_read_b64_tr_b16 v[76:77], v208 offset:40960
	ds_read_b64_tr_b16 v[78:79], v208 offset:43520
	ds_read_b64_tr_b16 v[82:83], v208 offset:43584
	ds_read_b64_tr_b16 v[80:81], v208 offset:41024
	s_setprio 1
	s_waitcnt lgkmcnt(4)
	v_mfma_f32_32x32x16_bf16 v[16:31], v[64:67], v[72:75], v[16:31]
	s_setprio 0
	s_setprio 1
	v_mfma_f32_32x32x16_bf16 v[0:15], v[68:71], v[72:75], v[0:15]
	s_setprio 0
	ds_read_b64_tr_b16 v[64:65], v208 offset:41088
	ds_read_b64_tr_b16 v[66:67], v208 offset:43648
	ds_read_b64_tr_b16 v[70:71], v208 offset:43712
	ds_read_b64_tr_b16 v[68:69], v208 offset:41152
	v_cvt_pk_bf16_f32 v72, v230, v231
	v_cvt_pk_bf16_f32 v73, v232, v233
	v_cvt_pk_bf16_f32 v74, v234, v235
	v_cvt_pk_bf16_f32 v75, v236, v237
	s_setprio 1
	s_nop 0
	s_waitcnt lgkmcnt(4)
	v_mfma_f32_32x32x16_bf16 v[48:63], v[76:79], v[72:75], v[48:63]
	s_setprio 0
	s_setprio 1
	v_mfma_f32_32x32x16_bf16 v[32:47], v[80:83], v[72:75], v[32:47]
	s_setprio 0
	s_setprio 1
	s_waitcnt lgkmcnt(0)
	v_mfma_f32_32x32x16_bf16 v[16:31], v[64:67], v[72:75], v[16:31]
	s_setprio 0
	s_setprio 1
	v_mfma_f32_32x32x16_bf16 v[0:15], v[68:71], v[72:75], v[0:15]
	s_setprio 0
	v_mov_b32_e32 v207, v242
	s_andn2_b64 vcc, exec, s[34:35]
	s_cbranch_vccz .LBB0_260
	s_branch .LBB0_261
